# P18: GEMM prologue first-tile waits and their barriers moved behind the per-step scalar job set-up (set-up overlaps the DMA latency); sixth prologue load issued before the first wait
# baseline (speedup 1.0000x reference)
; #define PG8_STAGE(bufoff, gbase, voff) do { _Pragma("unroll") for (int _i = 0; _i < 2; ++_i) { unsigned _vo = (voff)[_i]; asm volatile("" : "+v"(_vo));   \
;         __builtin_amdgcn_global_load_lds((const unsigned*)((const char*)(gbase) + _vo), (LAS unsigned*)(lds + (bufoff) + ldsw + _i * 8192), 16, 0, 0); } } while (0)
; #define PG8_WAIT_V(n) asm volatile("s_waitcnt vmcnt(" #n ")" ::: "memory")
; #define PG8_BAR __builtin_amdgcn_s_barrier()
; __device__ __forceinline__ void gemm_phase(LAS unsigned char* lds, const Call& C, const int tid, const Args& args) {
;     ...
;     if (wr == 1) PG8_BAR;
;     PG8_WAIT_V(2); PG8_BAR;
;     PG8_STAGE(PG8_SB(1, 0), cB + kstep, voffB); PG8_STAGE(PG8_SA(1, 0), cA + kstep, voffA); PG8_STAGE(PG8_SB(1, 1), cB + hstepB + kstep, voffB);
;     PG8_WAIT_V(6); PG8_BAR;
;     for (;;) {
;         next_unit(C, ui + 1, nxt.pm, nxt.pn, nxt.kp0, nxt.np, nxt.slice);
;         const bool has_next = nxt.pm >= 0;
;         const char* nA = has_next ? PG8_APTR(nxt) : cA; const char* nB = has_next ? PG8_BPTR(nxt) : cB;
;         const int nt = 2 * cur.np;
.LBB0_264:
	v_mov_b32_e32 v80, v242
	s_and_b32 s24, s12, 3
	s_lshl_b32 s27, s13, 6
	s_lshl_b32 s17, s13, 13
	s_lshl_b32 s13, s24, 5
	s_nop 0
	v_writelane_b32 v254, s13, 59
	s_lshl_b32 s13, s24, 12
	v_mov_b32_e32 v80, v242
	s_add_i32 m0, s20, 0x1e000
	s_cmpk_lt_u32 s5, 0x100
	v_mov_b32_e32 v80, v244
	s_cselect_b64 s[80:81], -1, 0
	s_bitcmp0_b32 s5, 6
	s_mov_b32 s97, s29
	v_lshl_add_u64 v[0:1], s[34:35], 0, v[80:81]
	s_cselect_b64 s[34:35], -1, 0
	s_lshl_b32 s25, s24, 4
	v_writelane_b32 v254, s34, 60
	s_add_i32 s25, s25, 0
	s_add_i32 s25, s25, 0x20400
	v_writelane_b32 v254, s35, 61
	s_lshl_b32 s12, s12, 5
	v_writelane_b32 v254, s25, 62
	s_cmp_lt_u32 s5, 64
	v_writelane_b32 v254, s12, 63
	s_cselect_b64 s[34:35], -1, 0
	v_writelane_b32 v255, s34, 0
	s_ashr_i32 s53, s11, 31
	s_ashr_i32 s51, s21, 31
	v_readlane_b32 s47, v254, 38
	s_lshl_b32 s12, s24, 6
	v_readlane_b32 s24, v254, 23
	v_writelane_b32 v255, s35, 1
	s_mul_i32 s5, s47, s42
	v_readlane_b32 s25, v254, 24
	s_add_u32 s12, s24, s12
	v_readlane_b32 s43, v254, 16
	v_writelane_b32 v255, s12, 2
	s_addc_u32 s12, s25, 0
	s_mul_i32 s5, s5, s43
	v_writelane_b32 v255, s12, 3
	s_add_i32 s54, s5, s26
	s_lshr_b32 s5, s26, 3
	s_and_b32 s88, s26, 7
	v_writelane_b32 v255, s5, 4
	s_add_i32 s5, s5, 1
	s_lshl_b32 s45, s43, 2
	s_add_u32 s24, s48, 0x1000
	v_writelane_b32 v255, s5, 5
	s_addc_u32 s25, s49, 0
	v_writelane_b32 v255, s24, 6
	v_readlane_b32 s5, v254, 52
	s_add_i32 s5, s27, s5
	v_writelane_b32 v255, s25, 7
	v_writelane_b32 v255, s27, 8
	v_writelane_b32 v255, s5, 9
	s_ashr_i32 s5, s44, 1
	v_lshl_add_u64 v[0:1], v[0:1], 0, s[18:19]
	s_and_b32 s12, s44, 1
	s_bfe_i32 s28, s44, 0x10000
	s_lshl_b32 s24, s5, 3
	global_load_lds_dwordx4 v[0:1], off
	s_bitcmp1_b32 s44, 0
	v_writelane_b32 v255, s24, 10
	s_cselect_b64 s[24:25], -1, 0
	s_cmp_lg_u32 s5, 3
	s_cselect_b64 s[34:35], -1, 0
	s_cmp_eq_u32 s12, 0
	s_cselect_b64 s[36:37], -1, 0
	s_and_b64 s[38:39], s[36:37], exec
	s_movk_i32 s12, 0x1400
	s_movk_i32 s27, 0xc00
	s_cselect_b32 s12, 0x800, s12
	s_cselect_b32 s38, 0x400, s27
	s_cselect_b32 s39, s94, 0x400
	s_cselect_b32 s40, 0xc00, 0
	s_cselect_b32 s41, 0x800, 0
	s_or_b64 s[34:35], s[36:37], s[34:35]
	v_writelane_b32 v255, s34, 11
	s_lshl_b32 s27, s44, 12
	s_mov_b32 s55, s29
	v_writelane_b32 v255, s35, 12
	s_xor_b64 s[34:35], s[34:35], -1
	v_writelane_b32 v255, s34, 13
	s_mov_b32 s92, 0
	s_movk_i32 s46, 0x1600
	v_writelane_b32 v255, s35, 14
	s_lshl_b32 s34, s5, 12
	s_or_b32 s34, s38, s34
	s_ashr_i32 s35, s34, 31
	s_lshl_b64 s[34:35], s[34:35], 2
	s_add_u32 s34, s68, s34
	v_writelane_b32 v255, s27, 15
	s_addc_u32 s35, s69, s35
	s_and_b32 s27, s28, 0x30000
	v_writelane_b32 v255, s34, 16
	s_cmp_lt_i32 s5, 3
	v_writelane_b32 v255, s35, 17
	s_cselect_b64 s[34:35], -1, 0
	s_and_b64 s[24:25], s[24:25], s[34:35]
	v_cndmask_b32_e64 v2, 0, 1, s[24:25]
	v_writelane_b32 v255, s27, 18
	v_readfirstlane_b32 s24, v2
	s_add_i32 s5, s5, s24
	s_lshl_b32 s5, s5, 12
	v_cvt_f32_u32_e32 v2, s42
	s_or_b32 s24, s5, s41
	s_ashr_i32 s25, s24, 31
	s_lshl_b64 s[24:25], s[24:25], 2
	s_add_u32 s24, s68, s24
	v_rcp_iflag_f32_e32 v3, v2
	s_addc_u32 s25, s69, s25
	v_writelane_b32 v255, s24, 19
	v_readlane_b32 s27, v254, 41
	v_mul_f32_e32 v4, 0x4f7ffffe, v3
	v_writelane_b32 v255, s25, 20
	s_add_u32 s24, s48, 0x2c00
	s_addc_u32 s25, s49, 0
	v_writelane_b32 v255, s24, 21
	v_cvt_u32_f32_e32 v4, v4
	s_nop 0
	v_writelane_b32 v255, s25, 22
	s_add_u32 s24, s48, 0x5800
	s_addc_u32 s25, s49, 0
	v_writelane_b32 v255, s24, 23
	s_sub_i32 s5, 0, s42
	s_lshl_b32 s96, s43, 8
	v_writelane_b32 v255, s25, 24
	v_readfirstlane_b32 s24, v4
	v_cvt_f32_u32_e32 v4, s27
	s_mul_i32 s5, s5, s24
	s_mul_hi_u32 s5, s24, s5
	s_add_i32 s5, s24, s5
	v_mul_f32_e32 v3, v4, v3
	v_trunc_f32_e32 v3, v3
	v_fma_f32 v4, -v3, v2, v4
	v_cvt_u32_f32_e32 v3, v3
	v_writelane_b32 v255, s5, 25
	s_lshl_b64 s[82:83], s[96:97], 8
	v_cmp_ge_f32_e64 s[24:25], |v4|, v2
	v_and_b32_e32 v2, 48, v204
	v_lshlrev_b32_e32 v4, 6, v204
	s_movk_i32 s5, 0x3c0
	s_cmp_lg_u64 s[24:25], 0
	v_and_or_b32 v2, v4, s5, v2
	v_readfirstlane_b32 s5, v3
	s_addc_u32 s5, s5, 0
	s_abs_i32 s97, s43
	v_cvt_f32_u32_e32 v3, s97
	v_lshlrev_b32_e32 v4, 2, v204
	v_and_b32_e32 v4, 32, v4
	s_abs_i32 s93, s45
	v_bitop3_b32 v5, v2, s17, v4 bitop3:0xde
	v_rcp_iflag_f32_e32 v3, v3
	v_bitop3_b32 v245, s13, v2, v4 bitop3:0xf6
	v_cvt_f32_u32_e32 v2, s93
	s_sub_i32 s13, 0, s97
	v_mul_f32_e32 v3, 0x4f7ffffe, v3
	v_cvt_u32_f32_e32 v3, v3
	v_rcp_iflag_f32_e32 v2, v2
	s_and_b32 s5, s5, 31
	v_add_u32_e32 v246, 0, v5
	v_readfirstlane_b32 s17, v3
	v_mul_f32_e32 v2, 0x4f7ffffe, v2
	v_cvt_u32_f32_e32 v2, v2
	s_mul_i32 s13, s13, s17
	s_mul_hi_u32 s13, s17, s13
	s_add_i32 s13, s17, s13
	v_writelane_b32 v255, s13, 26
	s_sub_i32 s13, 0, s93
	v_readfirstlane_b32 s17, v2
	s_mul_i32 s13, s13, s17
	s_mul_hi_u32 s13, s17, s13
	v_writelane_b32 v255, s45, 27
	s_add_i32 s13, s17, s13
	v_writelane_b32 v255, s13, 28
	v_writelane_b32 v255, s5, 29
	s_mul_i32 s5, s5, s42
	s_sub_i32 s5, s27, s5
	v_writelane_b32 v255, s5, 30
	s_ashr_i32 s5, s43, 31
	v_writelane_b32 v255, s5, 31
	s_bfe_i32 s5, s43, 0x1001d
	v_writelane_b32 v255, s5, 32
	s_add_u32 s89, s22, 0x80
	v_writelane_b32 v255, s54, 33
	s_addc_u32 s94, 0, 0
	s_lshl_b32 s5, s12, 2
	v_writelane_b32 v255, s55, 34
	v_writelane_b32 v255, s5, 35
	s_lshl_b32 s12, s40, 2
	v_writelane_b32 v255, s12, 36
	s_lshl_b32 s28, s39, 2
	s_mov_b32 s27, s29
	v_writelane_b32 v255, s13, 37
	v_readlane_b32 s55, v254, 15
	s_waitcnt vmcnt(8)
	s_barrier
	s_waitcnt vmcnt(6)
	s_barrier
	s_branch .LBB0_267
